# GU GEMM K-loop rewritten as 8-phase ping-pong schedule (waves 4-7 one barrier behind, quarter-tile LDS-DMA sub-buffers restaged as soon as free, 8 MFMA per phase, setprio 1 on MFMA part)
# speedup vs baseline: 1.0380x; 1.0380x over previous
.LBB0_53:
	s_mul_hi_i32 s2, s10, 0x2e8ba2e9
	s_lshr_b32 s3, s2, 31
	s_ashr_i32 s2, s2, 5
	s_add_i32 s17, s2, s3
	s_lshl_b32 s2, s17, 3
	s_sub_i32 s3, s0, s2
	s_min_i32 s3, s3, 8
	s_abs_i32 s14, s3
	v_cvt_f32_u32_e32 v2, s14
	s_sub_i32 s19, 0, s14
	s_mul_i32 s15, s17, 0xffffff50
	s_add_i32 s15, s15, s10
	v_rcp_iflag_f32_e32 v2, v2
	s_abs_i32 s16, s15
	s_xor_b32 s18, s15, s3
	s_ashr_i32 s18, s18, 31
	v_mul_f32_e32 v2, 0x4f7ffffe, v2
	v_cvt_u32_f32_e32 v2, v2
	s_mulk_i32 s17, 0xa8
	s_mov_b32 s4, 0x308d000
	s_mov_b32 s6, 0x30ad000
	v_readfirstlane_b32 s22, v2
	s_mul_i32 s19, s19, s22
	s_mul_hi_u32 s19, s22, s19
	s_add_i32 s22, s22, s19
	s_mul_hi_u32 s19, s16, s22
	s_mul_i32 s22, s19, s14
	s_sub_i32 s16, s16, s22
	s_add_i32 s23, s19, 1
	s_sub_i32 s22, s16, s14
	s_cmp_ge_u32 s16, s14
	s_cselect_b32 s19, s23, s19
	s_cselect_b32 s16, s22, s16
	s_add_i32 s22, s19, 1
	s_cmp_ge_u32 s16, s14
	s_cselect_b32 s14, s22, s19
	s_xor_b32 s14, s14, s18
	s_sub_i32 s16, s14, s18
	s_mul_i32 s18, s16, s3
	s_add_i32 s15, s15, s2
	s_sub_i32 s2, s15, s18
	s_lshl_b32 s14, s2, 8
	v_add_u32_e32 v2, s14, v164
	v_ashrrev_i32_e32 v3, 31, v2
	v_lshlrev_b64 v[2:3], 11, v[2:3]
	s_lshl_b32 s15, s16, 8
	v_lshl_add_u64 v[52:53], v[168:169], 0, v[2:3]
	s_mov_b32 s2, 0x20000
	v_add_u32_e32 v4, s15, v164
	v_add_co_u32_e32 v54, vcc, s2, v52
	v_ashrrev_i32_e32 v5, 31, v4
	s_nop 0
	v_addc_co_u32_e32 v55, vcc, 0, v53, vcc
	s_mov_b32 s3, 0x40000
	v_lshlrev_b64 v[48:49], 11, v[4:5]
	v_add_co_u32_e32 v56, vcc, s3, v52
	v_lshl_add_u64 v[50:51], v[166:167], 0, v[48:49]
	s_nop 0
	v_addc_co_u32_e32 v57, vcc, 0, v53, vcc
	v_add_co_u32_e32 v58, vcc, s2, v50
	s_mov_b32 s2, 0x60000
	s_nop 0
	v_addc_co_u32_e32 v59, vcc, 0, v51, vcc
	v_add_co_u32_e32 v60, vcc, s3, v50
	v_addc_co_u32_e32 v61, vcc, 0, v51, vcc
	v_add_co_u32_e32 v62, vcc, s2, v50
	v_addc_co_u32_e32 v63, vcc, 0, v51, vcc
	v_add_co_u32_e32 v64, vcc, s2, v52
	v_addc_co_u32_e32 v65, vcc, 0, v53, vcc
	s_sub_i32 s18, s10, s18
	s_sub_i32 s17, s18, s17
	s_lshl_b32 s18, s17, 8
	s_ashr_i32 s19, s18, 31
	v_lshl_add_u64 v[178:179], v[174:175], 0, v[48:49]
	v_lshl_add_u64 v[48:49], v[164:165], 0, s[18:19]
	v_mov_b32_e32 v2, 0
	v_lshlrev_b64 v[48:49], 11, v[48:49]
	s_mov_b32 s16, 1
	s_mov_b64 s[2:3], 0
	v_mov_b32_e32 v3, v2
	v_mov_b32_e32 v4, v2
	v_mov_b32_e32 v5, v2
	v_mov_b32_e32 v6, v2
	v_mov_b32_e32 v7, v2
	v_mov_b32_e32 v8, v2
	v_mov_b32_e32 v9, v2
	v_mov_b32_e32 v10, v2
	v_mov_b32_e32 v11, v2
	v_mov_b32_e32 v12, v2
	v_mov_b32_e32 v13, v2
	v_mov_b32_e32 v14, v2
	v_mov_b32_e32 v15, v2
	v_lshl_add_u64 v[180:181], v[176:177], 0, v[48:49]
	v_mov_b32_e32 v48, v2
	v_mov_b32_e32 v49, v2
	v_mov_b32_e32 v50, v2
	v_mov_b32_e32 v51, v2
	v_mov_b32_e32 v52, v2
	v_mov_b32_e32 v53, v2
	v_mov_b32_e32 v54, v2
	v_mov_b32_e32 v55, v2
	v_mov_b32_e32 v56, v2
	v_mov_b32_e32 v57, v2
	v_mov_b32_e32 v58, v2
	v_mov_b32_e32 v59, v2
	v_mov_b32_e32 v60, v2
	v_mov_b32_e32 v61, v2
	v_mov_b32_e32 v62, v2
	v_mov_b32_e32 v63, v2
	v_mov_b32_e32 v16, v2
	v_mov_b32_e32 v17, v2
	v_mov_b32_e32 v34, v2
	v_mov_b32_e32 v35, v2
	v_mov_b32_e32 v36, v2
	v_mov_b32_e32 v37, v2
	v_mov_b32_e32 v38, v2
	v_mov_b32_e32 v39, v2
	v_mov_b32_e32 v40, v2
	v_mov_b32_e32 v41, v2
	v_mov_b32_e32 v42, v2
	v_mov_b32_e32 v43, v2
	v_mov_b32_e32 v44, v2
	v_mov_b32_e32 v45, v2
	v_mov_b32_e32 v46, v2
	v_mov_b32_e32 v47, v2
	v_mov_b32_e32 v18, v2
	v_mov_b32_e32 v19, v2
	v_mov_b32_e32 v20, v2
	v_mov_b32_e32 v21, v2
	v_mov_b32_e32 v22, v2
	v_mov_b32_e32 v23, v2
	v_mov_b32_e32 v24, v2
	v_mov_b32_e32 v25, v2
	v_mov_b32_e32 v26, v2
	v_mov_b32_e32 v27, v2
	v_mov_b32_e32 v28, v2
	v_mov_b32_e32 v29, v2
	v_mov_b32_e32 v30, v2
	v_mov_b32_e32 v31, v2
	v_mov_b32_e32 v32, v2
	v_mov_b32_e32 v33, v2
	v_mov_b32_e32 v64, v2
	v_mov_b32_e32 v65, v2
	v_mov_b32_e32 v66, v2
	v_mov_b32_e32 v67, v2
	v_mov_b32_e32 v68, v2
	v_mov_b32_e32 v69, v2
	v_mov_b32_e32 v70, v2
	v_mov_b32_e32 v71, v2
	v_mov_b32_e32 v72, v2
	v_mov_b32_e32 v73, v2
	v_mov_b32_e32 v74, v2
	v_mov_b32_e32 v75, v2
	v_mov_b32_e32 v76, v2
	v_mov_b32_e32 v77, v2
	v_mov_b32_e32 v78, v2
	v_mov_b32_e32 v79, v2
	v_mov_b32_e32 v80, v2
	v_mov_b32_e32 v81, v2
	v_mov_b32_e32 v98, v2
	v_mov_b32_e32 v99, v2
	v_mov_b32_e32 v100, v2
	v_mov_b32_e32 v101, v2
	v_mov_b32_e32 v102, v2
	v_mov_b32_e32 v103, v2
	v_mov_b32_e32 v104, v2
	v_mov_b32_e32 v105, v2
	v_mov_b32_e32 v106, v2
	v_mov_b32_e32 v107, v2
	v_mov_b32_e32 v108, v2
	v_mov_b32_e32 v109, v2
	v_mov_b32_e32 v110, v2
	v_mov_b32_e32 v111, v2
	v_mov_b32_e32 v112, v2
	v_mov_b32_e32 v113, v2
	v_mov_b32_e32 v82, v2
	v_mov_b32_e32 v83, v2
	v_mov_b32_e32 v84, v2
	v_mov_b32_e32 v85, v2
	v_mov_b32_e32 v86, v2
	v_mov_b32_e32 v87, v2
	v_mov_b32_e32 v88, v2
	v_mov_b32_e32 v89, v2
	v_mov_b32_e32 v90, v2
	v_mov_b32_e32 v91, v2
	v_mov_b32_e32 v92, v2
	v_mov_b32_e32 v93, v2
	v_mov_b32_e32 v94, v2
	v_mov_b32_e32 v95, v2
	v_mov_b32_e32 v96, v2
	v_mov_b32_e32 v97, v2
	v_mov_b32_e32 v114, v2
	v_mov_b32_e32 v115, v2
	v_mov_b32_e32 v116, v2
	v_mov_b32_e32 v117, v2
	v_mov_b32_e32 v118, v2
	v_mov_b32_e32 v119, v2
	v_mov_b32_e32 v120, v2
	v_mov_b32_e32 v121, v2
	v_mov_b32_e32 v122, v2
	v_mov_b32_e32 v123, v2
	v_mov_b32_e32 v124, v2
	v_mov_b32_e32 v125, v2
	v_mov_b32_e32 v126, v2
	v_mov_b32_e32 v127, v2
	v_mov_b32_e32 v128, v2
	v_mov_b32_e32 v129, v2
	s_mov_b32 s7, 0x30cd000
	s_waitcnt lgkmcnt(0)
	v_lshrrev_b32_e32 v130, 6, v200
	v_and_b32_e32 v131, 63, v200
	v_readfirstlane_b32 s17, v130
	s_lshr_b32 s18, s17, 2
	s_and_b32 s19, s17, 3
	s_lshl_b32 s19, s19, 4
	s_lshl_b32 s4, s18, 7
	s_add_u32 s4, s4, s19
	s_add_u32 s19, s4, s14
	s_mul_i32 s19, s19, 2048
	s_add_u32 s2, s36, 0x308d800
	s_addc_u32 s3, s37, 0
	s_add_u32 s2, s2, s19
	s_addc_u32 s3, s3, 0
	s_lshl_b32 s4, s4, 7
	s_lshr_b32 s16, s17, 1
	s_lshl_b32 s16, s16, 6
	s_and_b32 s19, s17, 1
	s_lshl_b32 s19, s19, 4
	s_add_u32 s16, s16, s19
	s_add_u32 s19, s16, s15
	s_mul_i32 s19, s19, 2048
	v_readlane_b32 s7, v255, 30
	s_nop 3
	s_mul_i32 s7, s7, 0xb00000
	s_add_u32 s6, s36, s7
	s_addc_u32 s7, s37, 0
	s_add_u32 s6, s6, 0xc6d800
	s_addc_u32 s7, s7, 0
	s_add_u32 s6, s6, s19
	s_addc_u32 s7, s7, 0
	s_lshl_b32 s16, s16, 7
	s_add_u32 s16, s16, 0x10000
	v_lshrrev_b32_e32 v132, 3, v131
	v_and_b32_e32 v133, 7, v131
	v_lshrrev_b32_e32 v134, 4, v131
	v_xor_b32_e32 v133, v133, v134
	v_lshlrev_b32_e32 v133, 4, v133
	v_mul_u32_u24_e32 v134, 2048, v132
	v_or_b32_e32 v246, v134, v133
	v_add_u32_e32 v247, 16384, v246
	v_xor_b32_e32 v247, 64, v247
	v_add_u32_e32 v248, 0x20000, v246
	v_add_u32_e32 v249, 0x20000, v247
	v_mul_u32_u24_e32 v134, 2048, v132
	v_or_b32_e32 v250, v134, v133
	v_add_u32_e32 v251, 16384, v250
	v_xor_b32_e32 v251, 64, v251
	v_add_u32_e32 v252, 0x10000, v250
	v_add_u32_e32 v214, 0x10000, v251
	v_and_b32_e32 v132, 31, v131
	v_lshrrev_b32_e32 v133, 5, v131
	v_bfe_u32 v134, v132, 1, 3
	v_and_b32_e32 v135, 1, v134
	v_xor_b32_e32 v133, v133, v135
	v_lshlrev_b32_e32 v133, 4, v133
	v_lshl_add_u32 v133, v132, 7, v133
	v_and_b32_e32 v134, 6, v134
	s_lshl_b32 s19, s18, 14
	s_and_b32 s17, s17, 3
	s_lshl_b32 s17, s17, 13
	s_add_u32 s17, s17, 0x10000
	v_xor_b32_e32 v135, 0, v134
	v_lshl_add_u32 v135, v135, 4, v133
	v_add_u32_e32 v238, s19, v135
	v_add_u32_e32 v242, s17, v135
	v_xor_b32_e32 v135, 2, v134
	v_lshl_add_u32 v135, v135, 4, v133
	v_add_u32_e32 v239, s19, v135
	v_add_u32_e32 v243, s17, v135
	v_xor_b32_e32 v135, 4, v134
	v_lshl_add_u32 v135, v135, 4, v133
	v_add_u32_e32 v240, s19, v135
	v_add_u32_e32 v244, s17, v135
	v_xor_b32_e32 v135, 6, v134
	v_lshl_add_u32 v135, v135, 4, v133
	v_add_u32_e32 v241, s19, v135
	v_add_u32_e32 v245, s17, v135
	s_add_u32 m0, s16, 0x0
	s_nop 0
	global_load_lds_dwordx4 v250, s[6:7]
	s_add_u32 m0, s16, 0x400
	s_nop 0
	global_load_lds_dwordx4 v251, s[6:7]
	s_add_u32 m0, s4, 0x0
	s_nop 0
	global_load_lds_dwordx4 v246, s[2:3]
	s_add_u32 m0, s4, 0x400
	s_nop 0
	global_load_lds_dwordx4 v247, s[2:3]
	s_add_u32 m0, s16, 0x1000
	s_nop 0
	global_load_lds_dwordx4 v252, s[6:7]
	s_add_u32 m0, s16, 0x1400
	s_nop 0
	global_load_lds_dwordx4 v214, s[6:7]
	s_add_u32 m0, s4, 0x2000
	s_nop 0
	global_load_lds_dwordx4 v248, s[2:3]
	s_add_u32 m0, s4, 0x2400
	s_nop 0
	global_load_lds_dwordx4 v249, s[2:3]
	s_cmp_lg_u32 s18, 0
	s_cbranch_scc0 .Lggu_nolag
	s_barrier
.Lggu_nolag:
	s_waitcnt vmcnt(4)
	s_barrier
	s_add_u32 s6, s6, 0x80
	s_addc_u32 s7, s7, 0
	s_add_u32 m0, s16, 0x8000
	s_nop 0
	global_load_lds_dwordx4 v250, s[6:7]
	s_add_u32 m0, s16, 0x8400
	s_nop 0
	global_load_lds_dwordx4 v251, s[6:7]
	s_add_u32 s2, s2, 0x80
	s_addc_u32 s3, s3, 0
	s_add_u32 m0, s4, 0x8000
	s_nop 0
	global_load_lds_dwordx4 v246, s[2:3]
	s_add_u32 m0, s4, 0x8400
	s_nop 0
	global_load_lds_dwordx4 v247, s[2:3]
	s_add_u32 m0, s16, 0x9000
	s_nop 0
	global_load_lds_dwordx4 v252, s[6:7]
	s_add_u32 m0, s16, 0x9400
	s_nop 0
	global_load_lds_dwordx4 v214, s[6:7]
	s_waitcnt vmcnt(6)
	s_barrier
	s_mov_b32 s17, 0
.Lggu_loop:
	ds_read_b128 v[192:195], v242
	ds_read_b128 v[196:199], v243
	ds_read_b128 v[208:211], v244
	ds_read_b128 v[218:221], v245
	ds_read_b128 v[130:133], v238 offset:0
	ds_read_b128 v[134:137], v239 offset:0
	ds_read_b128 v[138:141], v240 offset:0
	ds_read_b128 v[142:145], v241 offset:0
	ds_read_b128 v[146:149], v238 offset:4096
	ds_read_b128 v[150:153], v239 offset:4096
	ds_read_b128 v[154:157], v240 offset:4096
	ds_read_b128 v[158:161], v241 offset:4096
	s_add_u32 m0, s4, 0xa000
	s_nop 0
	global_load_lds_dwordx4 v248, s[2:3]
	s_add_u32 m0, s4, 0xa400
	s_nop 0
	global_load_lds_dwordx4 v249, s[2:3]
	s_waitcnt lgkmcnt(8)
	s_barrier
	s_waitcnt lgkmcnt(0)
	s_setprio 1
	v_mfma_f32_32x32x16_bf16 v[114:129], v[192:195], v[130:133], v[114:129]
	v_mfma_f32_32x32x16_bf16 v[82:97], v[192:195], v[146:149], v[82:97]
	v_mfma_f32_32x32x16_bf16 v[114:129], v[196:199], v[134:137], v[114:129]
	v_mfma_f32_32x32x16_bf16 v[82:97], v[196:199], v[150:153], v[82:97]
	v_mfma_f32_32x32x16_bf16 v[114:129], v[208:211], v[138:141], v[114:129]
	v_mfma_f32_32x32x16_bf16 v[82:97], v[208:211], v[154:157], v[82:97]
	v_mfma_f32_32x32x16_bf16 v[114:129], v[218:221], v[142:145], v[114:129]
	v_mfma_f32_32x32x16_bf16 v[82:97], v[218:221], v[158:161], v[82:97]
	s_setprio 0
	s_barrier
	ds_read_b128 v[222:225], v242 offset:4096
	ds_read_b128 v[226:229], v243 offset:4096
	ds_read_b128 v[230:233], v244 offset:4096
	ds_read_b128 v[234:237], v245 offset:4096
	s_add_u32 s6, s6, 0x80
	s_addc_u32 s7, s7, 0
	s_add_u32 m0, s16, 0x0
	s_nop 0
	global_load_lds_dwordx4 v250, s[6:7]
	s_add_u32 m0, s16, 0x400
	s_nop 0
	global_load_lds_dwordx4 v251, s[6:7]
	s_barrier
	s_waitcnt lgkmcnt(0)
	s_setprio 1
	v_mfma_f32_32x32x16_bf16 v[98:113], v[222:225], v[130:133], v[98:113]
	v_mfma_f32_32x32x16_bf16 v[66:81], v[222:225], v[146:149], v[66:81]
	v_mfma_f32_32x32x16_bf16 v[98:113], v[226:229], v[134:137], v[98:113]
	v_mfma_f32_32x32x16_bf16 v[66:81], v[226:229], v[150:153], v[66:81]
	v_mfma_f32_32x32x16_bf16 v[98:113], v[230:233], v[138:141], v[98:113]
	v_mfma_f32_32x32x16_bf16 v[66:81], v[230:233], v[154:157], v[66:81]
	v_mfma_f32_32x32x16_bf16 v[98:113], v[234:237], v[142:145], v[98:113]
	v_mfma_f32_32x32x16_bf16 v[66:81], v[234:237], v[158:161], v[66:81]
	s_setprio 0
	s_barrier
	ds_read_b128 v[130:133], v238 offset:8192
	ds_read_b128 v[134:137], v239 offset:8192
	ds_read_b128 v[138:141], v240 offset:8192
	ds_read_b128 v[142:145], v241 offset:8192
	ds_read_b128 v[146:149], v238 offset:12288
	ds_read_b128 v[150:153], v239 offset:12288
	ds_read_b128 v[154:157], v240 offset:12288
	ds_read_b128 v[158:161], v241 offset:12288
	s_add_u32 s2, s2, 0x80
	s_addc_u32 s3, s3, 0
	s_add_u32 m0, s4, 0x0
	s_nop 0
	global_load_lds_dwordx4 v246, s[2:3]
	s_add_u32 m0, s4, 0x400
	s_nop 0
	global_load_lds_dwordx4 v247, s[2:3]
	s_barrier
	s_waitcnt lgkmcnt(0)
	s_setprio 1
	v_mfma_f32_32x32x16_bf16 v[50:65], v[192:195], v[130:133], v[50:65]
	v_mfma_f32_32x32x16_bf16 v[18:33], v[192:195], v[146:149], v[18:33]
	v_mfma_f32_32x32x16_bf16 v[50:65], v[196:199], v[134:137], v[50:65]
	v_mfma_f32_32x32x16_bf16 v[18:33], v[196:199], v[150:153], v[18:33]
	v_mfma_f32_32x32x16_bf16 v[50:65], v[208:211], v[138:141], v[50:65]
	v_mfma_f32_32x32x16_bf16 v[18:33], v[208:211], v[154:157], v[18:33]
	v_mfma_f32_32x32x16_bf16 v[50:65], v[218:221], v[142:145], v[50:65]
	v_mfma_f32_32x32x16_bf16 v[18:33], v[218:221], v[158:161], v[18:33]
	s_setprio 0
	s_barrier
	s_add_u32 m0, s16, 0x1000
	s_nop 0
	global_load_lds_dwordx4 v252, s[6:7]
	s_add_u32 m0, s16, 0x1400
	s_nop 0
	global_load_lds_dwordx4 v214, s[6:7]
	s_waitcnt vmcnt(6)
	s_barrier
	s_setprio 1
	v_mfma_f32_32x32x16_bf16 v[34:49], v[222:225], v[130:133], v[34:49]
	v_mfma_f32_32x32x16_bf16 v[2:17], v[222:225], v[146:149], v[2:17]
	v_mfma_f32_32x32x16_bf16 v[34:49], v[226:229], v[134:137], v[34:49]
	v_mfma_f32_32x32x16_bf16 v[2:17], v[226:229], v[150:153], v[2:17]
	v_mfma_f32_32x32x16_bf16 v[34:49], v[230:233], v[138:141], v[34:49]
	v_mfma_f32_32x32x16_bf16 v[2:17], v[230:233], v[154:157], v[2:17]
	v_mfma_f32_32x32x16_bf16 v[34:49], v[234:237], v[142:145], v[34:49]
	v_mfma_f32_32x32x16_bf16 v[2:17], v[234:237], v[158:161], v[2:17]
	s_setprio 0
	s_barrier
	ds_read_b128 v[192:195], v242 offset:32768
	ds_read_b128 v[196:199], v243 offset:32768
	ds_read_b128 v[208:211], v244 offset:32768
	ds_read_b128 v[218:221], v245 offset:32768
	ds_read_b128 v[130:133], v238 offset:32768
	ds_read_b128 v[134:137], v239 offset:32768
	ds_read_b128 v[138:141], v240 offset:32768
	ds_read_b128 v[142:145], v241 offset:32768
	ds_read_b128 v[146:149], v238 offset:36864
	ds_read_b128 v[150:153], v239 offset:36864
	ds_read_b128 v[154:157], v240 offset:36864
	ds_read_b128 v[158:161], v241 offset:36864
	s_add_u32 m0, s4, 0x2000
	s_nop 0
	global_load_lds_dwordx4 v248, s[2:3]
	s_add_u32 m0, s4, 0x2400
	s_nop 0
	global_load_lds_dwordx4 v249, s[2:3]
	s_waitcnt lgkmcnt(8)
	s_barrier
	s_waitcnt lgkmcnt(0)
	s_setprio 1
	v_mfma_f32_32x32x16_bf16 v[114:129], v[192:195], v[130:133], v[114:129]
	v_mfma_f32_32x32x16_bf16 v[82:97], v[192:195], v[146:149], v[82:97]
	v_mfma_f32_32x32x16_bf16 v[114:129], v[196:199], v[134:137], v[114:129]
	v_mfma_f32_32x32x16_bf16 v[82:97], v[196:199], v[150:153], v[82:97]
	v_mfma_f32_32x32x16_bf16 v[114:129], v[208:211], v[138:141], v[114:129]
	v_mfma_f32_32x32x16_bf16 v[82:97], v[208:211], v[154:157], v[82:97]
	v_mfma_f32_32x32x16_bf16 v[114:129], v[218:221], v[142:145], v[114:129]
	v_mfma_f32_32x32x16_bf16 v[82:97], v[218:221], v[158:161], v[82:97]
	s_setprio 0
	s_barrier
	ds_read_b128 v[222:225], v242 offset:36864
	ds_read_b128 v[226:229], v243 offset:36864
	ds_read_b128 v[230:233], v244 offset:36864
	ds_read_b128 v[234:237], v245 offset:36864
	s_add_u32 s6, s6, 0x80
	s_addc_u32 s7, s7, 0
	s_add_u32 m0, s16, 0x8000
	s_nop 0
	global_load_lds_dwordx4 v250, s[6:7]
	s_add_u32 m0, s16, 0x8400
	s_nop 0
	global_load_lds_dwordx4 v251, s[6:7]
	s_barrier
	s_waitcnt lgkmcnt(0)
	s_setprio 1
	v_mfma_f32_32x32x16_bf16 v[98:113], v[222:225], v[130:133], v[98:113]
	v_mfma_f32_32x32x16_bf16 v[66:81], v[222:225], v[146:149], v[66:81]
	v_mfma_f32_32x32x16_bf16 v[98:113], v[226:229], v[134:137], v[98:113]
	v_mfma_f32_32x32x16_bf16 v[66:81], v[226:229], v[150:153], v[66:81]
	v_mfma_f32_32x32x16_bf16 v[98:113], v[230:233], v[138:141], v[98:113]
	v_mfma_f32_32x32x16_bf16 v[66:81], v[230:233], v[154:157], v[66:81]
	v_mfma_f32_32x32x16_bf16 v[98:113], v[234:237], v[142:145], v[98:113]
	v_mfma_f32_32x32x16_bf16 v[66:81], v[234:237], v[158:161], v[66:81]
	s_setprio 0
	s_barrier
	ds_read_b128 v[130:133], v238 offset:40960
	ds_read_b128 v[134:137], v239 offset:40960
	ds_read_b128 v[138:141], v240 offset:40960
	ds_read_b128 v[142:145], v241 offset:40960
	ds_read_b128 v[146:149], v238 offset:45056
	ds_read_b128 v[150:153], v239 offset:45056
	ds_read_b128 v[154:157], v240 offset:45056
	ds_read_b128 v[158:161], v241 offset:45056
	s_add_u32 s2, s2, 0x80
	s_addc_u32 s3, s3, 0
	s_add_u32 m0, s4, 0x8000
	s_nop 0
	global_load_lds_dwordx4 v246, s[2:3]
	s_add_u32 m0, s4, 0x8400
	s_nop 0
	global_load_lds_dwordx4 v247, s[2:3]
	s_barrier
	s_waitcnt lgkmcnt(0)
	s_setprio 1
	v_mfma_f32_32x32x16_bf16 v[50:65], v[192:195], v[130:133], v[50:65]
	v_mfma_f32_32x32x16_bf16 v[18:33], v[192:195], v[146:149], v[18:33]
	v_mfma_f32_32x32x16_bf16 v[50:65], v[196:199], v[134:137], v[50:65]
	v_mfma_f32_32x32x16_bf16 v[18:33], v[196:199], v[150:153], v[18:33]
	v_mfma_f32_32x32x16_bf16 v[50:65], v[208:211], v[138:141], v[50:65]
	v_mfma_f32_32x32x16_bf16 v[18:33], v[208:211], v[154:157], v[18:33]
	v_mfma_f32_32x32x16_bf16 v[50:65], v[218:221], v[142:145], v[50:65]
	v_mfma_f32_32x32x16_bf16 v[18:33], v[218:221], v[158:161], v[18:33]
	s_setprio 0
	s_barrier
	s_add_u32 m0, s16, 0x9000
	s_nop 0
	global_load_lds_dwordx4 v252, s[6:7]
	s_add_u32 m0, s16, 0x9400
	s_nop 0
	global_load_lds_dwordx4 v214, s[6:7]
	s_waitcnt vmcnt(6)
	s_barrier
	s_setprio 1
	v_mfma_f32_32x32x16_bf16 v[34:49], v[222:225], v[130:133], v[34:49]
	v_mfma_f32_32x32x16_bf16 v[2:17], v[222:225], v[146:149], v[2:17]
	v_mfma_f32_32x32x16_bf16 v[34:49], v[226:229], v[134:137], v[34:49]
	v_mfma_f32_32x32x16_bf16 v[2:17], v[226:229], v[150:153], v[2:17]
	v_mfma_f32_32x32x16_bf16 v[34:49], v[230:233], v[138:141], v[34:49]
	v_mfma_f32_32x32x16_bf16 v[2:17], v[230:233], v[154:157], v[2:17]
	v_mfma_f32_32x32x16_bf16 v[34:49], v[234:237], v[142:145], v[34:49]
	v_mfma_f32_32x32x16_bf16 v[2:17], v[234:237], v[158:161], v[2:17]
	s_setprio 0
	s_barrier
	s_add_i32 s17, s17, 2
	s_cmp_lt_u32 s17, 14
	s_cbranch_scc1 .Lggu_loop
	ds_read_b128 v[192:195], v242
	ds_read_b128 v[196:199], v243
	ds_read_b128 v[208:211], v244
	ds_read_b128 v[218:221], v245
	ds_read_b128 v[130:133], v238 offset:0
	ds_read_b128 v[134:137], v239 offset:0
	ds_read_b128 v[138:141], v240 offset:0
	ds_read_b128 v[142:145], v241 offset:0
	ds_read_b128 v[146:149], v238 offset:4096
	ds_read_b128 v[150:153], v239 offset:4096
	ds_read_b128 v[154:157], v240 offset:4096
	ds_read_b128 v[158:161], v241 offset:4096
	s_add_u32 m0, s4, 0xa000
	s_nop 0
	global_load_lds_dwordx4 v248, s[2:3]
	s_add_u32 m0, s4, 0xa400
	s_nop 0
	global_load_lds_dwordx4 v249, s[2:3]
	s_barrier
	s_waitcnt lgkmcnt(0)
	s_setprio 1
	v_mfma_f32_32x32x16_bf16 v[114:129], v[192:195], v[130:133], v[114:129]
	v_mfma_f32_32x32x16_bf16 v[82:97], v[192:195], v[146:149], v[82:97]
	v_mfma_f32_32x32x16_bf16 v[114:129], v[196:199], v[134:137], v[114:129]
	v_mfma_f32_32x32x16_bf16 v[82:97], v[196:199], v[150:153], v[82:97]
	v_mfma_f32_32x32x16_bf16 v[114:129], v[208:211], v[138:141], v[114:129]
	v_mfma_f32_32x32x16_bf16 v[82:97], v[208:211], v[154:157], v[82:97]
	v_mfma_f32_32x32x16_bf16 v[114:129], v[218:221], v[142:145], v[114:129]
	v_mfma_f32_32x32x16_bf16 v[82:97], v[218:221], v[158:161], v[82:97]
	s_setprio 0
	s_barrier
	ds_read_b128 v[222:225], v242 offset:4096
	ds_read_b128 v[226:229], v243 offset:4096
	ds_read_b128 v[230:233], v244 offset:4096
	ds_read_b128 v[234:237], v245 offset:4096
	s_barrier
	s_waitcnt lgkmcnt(0)
	s_setprio 1
	v_mfma_f32_32x32x16_bf16 v[98:113], v[222:225], v[130:133], v[98:113]
	v_mfma_f32_32x32x16_bf16 v[66:81], v[222:225], v[146:149], v[66:81]
	v_mfma_f32_32x32x16_bf16 v[98:113], v[226:229], v[134:137], v[98:113]
	v_mfma_f32_32x32x16_bf16 v[66:81], v[226:229], v[150:153], v[66:81]
	v_mfma_f32_32x32x16_bf16 v[98:113], v[230:233], v[138:141], v[98:113]
	v_mfma_f32_32x32x16_bf16 v[66:81], v[230:233], v[154:157], v[66:81]
	v_mfma_f32_32x32x16_bf16 v[98:113], v[234:237], v[142:145], v[98:113]
	v_mfma_f32_32x32x16_bf16 v[66:81], v[234:237], v[158:161], v[66:81]
	s_setprio 0
	s_barrier
	ds_read_b128 v[130:133], v238 offset:8192
	ds_read_b128 v[134:137], v239 offset:8192
	ds_read_b128 v[138:141], v240 offset:8192
	ds_read_b128 v[142:145], v241 offset:8192
	ds_read_b128 v[146:149], v238 offset:12288
	ds_read_b128 v[150:153], v239 offset:12288
	ds_read_b128 v[154:157], v240 offset:12288
	ds_read_b128 v[158:161], v241 offset:12288
	s_waitcnt vmcnt(4)
	s_barrier
	s_waitcnt lgkmcnt(0)
	s_setprio 1
	v_mfma_f32_32x32x16_bf16 v[50:65], v[192:195], v[130:133], v[50:65]
	v_mfma_f32_32x32x16_bf16 v[18:33], v[192:195], v[146:149], v[18:33]
	v_mfma_f32_32x32x16_bf16 v[50:65], v[196:199], v[134:137], v[50:65]
	v_mfma_f32_32x32x16_bf16 v[18:33], v[196:199], v[150:153], v[18:33]
	v_mfma_f32_32x32x16_bf16 v[50:65], v[208:211], v[138:141], v[50:65]
	v_mfma_f32_32x32x16_bf16 v[18:33], v[208:211], v[154:157], v[18:33]
	v_mfma_f32_32x32x16_bf16 v[50:65], v[218:221], v[142:145], v[50:65]
	v_mfma_f32_32x32x16_bf16 v[18:33], v[218:221], v[158:161], v[18:33]
	s_setprio 0
	s_setprio 1
	v_mfma_f32_32x32x16_bf16 v[34:49], v[222:225], v[130:133], v[34:49]
	v_mfma_f32_32x32x16_bf16 v[2:17], v[222:225], v[146:149], v[2:17]
	v_mfma_f32_32x32x16_bf16 v[34:49], v[226:229], v[134:137], v[34:49]
	v_mfma_f32_32x32x16_bf16 v[2:17], v[226:229], v[150:153], v[2:17]
	v_mfma_f32_32x32x16_bf16 v[34:49], v[230:233], v[138:141], v[34:49]
	v_mfma_f32_32x32x16_bf16 v[2:17], v[230:233], v[154:157], v[2:17]
	v_mfma_f32_32x32x16_bf16 v[34:49], v[234:237], v[142:145], v[34:49]
	v_mfma_f32_32x32x16_bf16 v[2:17], v[234:237], v[158:161], v[2:17]
	s_setprio 0
	s_barrier
	ds_read_b128 v[192:195], v242 offset:32768
	ds_read_b128 v[196:199], v243 offset:32768
	ds_read_b128 v[208:211], v244 offset:32768
	ds_read_b128 v[218:221], v245 offset:32768
	ds_read_b128 v[130:133], v238 offset:32768
	ds_read_b128 v[134:137], v239 offset:32768
	ds_read_b128 v[138:141], v240 offset:32768
	ds_read_b128 v[142:145], v241 offset:32768
	ds_read_b128 v[146:149], v238 offset:36864
	ds_read_b128 v[150:153], v239 offset:36864
	ds_read_b128 v[154:157], v240 offset:36864
	ds_read_b128 v[158:161], v241 offset:36864
	s_waitcnt vmcnt(2)
	s_barrier
	s_waitcnt lgkmcnt(0)
	s_setprio 1
	v_mfma_f32_32x32x16_bf16 v[114:129], v[192:195], v[130:133], v[114:129]
	v_mfma_f32_32x32x16_bf16 v[82:97], v[192:195], v[146:149], v[82:97]
	v_mfma_f32_32x32x16_bf16 v[114:129], v[196:199], v[134:137], v[114:129]
	v_mfma_f32_32x32x16_bf16 v[82:97], v[196:199], v[150:153], v[82:97]
	v_mfma_f32_32x32x16_bf16 v[114:129], v[208:211], v[138:141], v[114:129]
	v_mfma_f32_32x32x16_bf16 v[82:97], v[208:211], v[154:157], v[82:97]
	v_mfma_f32_32x32x16_bf16 v[114:129], v[218:221], v[142:145], v[114:129]
	v_mfma_f32_32x32x16_bf16 v[82:97], v[218:221], v[158:161], v[82:97]
	s_setprio 0
	s_barrier
	ds_read_b128 v[222:225], v242 offset:36864
	ds_read_b128 v[226:229], v243 offset:36864
	ds_read_b128 v[230:233], v244 offset:36864
	ds_read_b128 v[234:237], v245 offset:36864
	s_waitcnt vmcnt(0)
	s_barrier
	s_waitcnt lgkmcnt(0)
	s_setprio 1
	v_mfma_f32_32x32x16_bf16 v[98:113], v[222:225], v[130:133], v[98:113]
	v_mfma_f32_32x32x16_bf16 v[66:81], v[222:225], v[146:149], v[66:81]
	v_mfma_f32_32x32x16_bf16 v[98:113], v[226:229], v[134:137], v[98:113]
	v_mfma_f32_32x32x16_bf16 v[66:81], v[226:229], v[150:153], v[66:81]
	v_mfma_f32_32x32x16_bf16 v[98:113], v[230:233], v[138:141], v[98:113]
	v_mfma_f32_32x32x16_bf16 v[66:81], v[230:233], v[154:157], v[66:81]
	v_mfma_f32_32x32x16_bf16 v[98:113], v[234:237], v[142:145], v[98:113]
	v_mfma_f32_32x32x16_bf16 v[66:81], v[234:237], v[158:161], v[66:81]
	s_setprio 0
	s_barrier
	ds_read_b128 v[130:133], v238 offset:40960
	ds_read_b128 v[134:137], v239 offset:40960
	ds_read_b128 v[138:141], v240 offset:40960
	ds_read_b128 v[142:145], v241 offset:40960
	ds_read_b128 v[146:149], v238 offset:45056
	ds_read_b128 v[150:153], v239 offset:45056
	ds_read_b128 v[154:157], v240 offset:45056
	ds_read_b128 v[158:161], v241 offset:45056
	s_barrier
	s_waitcnt lgkmcnt(0)
	s_setprio 1
	v_mfma_f32_32x32x16_bf16 v[50:65], v[192:195], v[130:133], v[50:65]
	v_mfma_f32_32x32x16_bf16 v[18:33], v[192:195], v[146:149], v[18:33]
	v_mfma_f32_32x32x16_bf16 v[50:65], v[196:199], v[134:137], v[50:65]
	v_mfma_f32_32x32x16_bf16 v[18:33], v[196:199], v[150:153], v[18:33]
	v_mfma_f32_32x32x16_bf16 v[50:65], v[208:211], v[138:141], v[50:65]
	v_mfma_f32_32x32x16_bf16 v[18:33], v[208:211], v[154:157], v[18:33]
	v_mfma_f32_32x32x16_bf16 v[50:65], v[218:221], v[142:145], v[50:65]
	v_mfma_f32_32x32x16_bf16 v[18:33], v[218:221], v[158:161], v[18:33]
	s_setprio 0
	s_setprio 1
	v_mfma_f32_32x32x16_bf16 v[34:49], v[222:225], v[130:133], v[34:49]
	v_mfma_f32_32x32x16_bf16 v[2:17], v[222:225], v[146:149], v[2:17]
	v_mfma_f32_32x32x16_bf16 v[34:49], v[226:229], v[134:137], v[34:49]
	v_mfma_f32_32x32x16_bf16 v[2:17], v[226:229], v[150:153], v[2:17]
	v_mfma_f32_32x32x16_bf16 v[34:49], v[230:233], v[138:141], v[34:49]
	v_mfma_f32_32x32x16_bf16 v[2:17], v[230:233], v[154:157], v[2:17]
	v_mfma_f32_32x32x16_bf16 v[34:49], v[234:237], v[142:145], v[34:49]
	v_mfma_f32_32x32x16_bf16 v[2:17], v[234:237], v[158:161], v[2:17]
	s_setprio 0
	s_barrier
	s_cmp_lg_u32 s18, 0
	s_cbranch_scc1 .Lggu_nolag2
	s_barrier
.Lggu_nolag2:
	s_nop 15
	s_nop 15
	s_waitcnt lgkmcnt(3)
	s_waitcnt lgkmcnt(2)
	s_waitcnt lgkmcnt(1)
	s_waitcnt lgkmcnt(0)
	s_waitcnt lgkmcnt(0)
	s_waitcnt lgkmcnt(3)
	s_waitcnt lgkmcnt(2)
	s_waitcnt lgkmcnt(1)
	s_waitcnt lgkmcnt(0)
	s_waitcnt lgkmcnt(0)
	s_waitcnt lgkmcnt(3)
	s_waitcnt lgkmcnt(2)
	s_waitcnt lgkmcnt(1)
	s_waitcnt lgkmcnt(0)
	s_waitcnt lgkmcnt(0)
	v_add_u32_e32 v150, 0x12000, v170
	s_waitcnt lgkmcnt(3)
	s_waitcnt lgkmcnt(2)
	s_waitcnt lgkmcnt(1)
	s_waitcnt lgkmcnt(0)
	s_waitcnt lgkmcnt(0)
	s_waitcnt lgkmcnt(1)
	s_waitcnt lgkmcnt(0)
	s_waitcnt lgkmcnt(0)
	s_waitcnt lgkmcnt(3)
	s_waitcnt lgkmcnt(2)
	s_waitcnt lgkmcnt(1)
	s_waitcnt lgkmcnt(0)
	s_waitcnt lgkmcnt(0)
	s_waitcnt lgkmcnt(3)
	s_waitcnt lgkmcnt(2)
	s_waitcnt lgkmcnt(1)
	s_waitcnt lgkmcnt(0)
	s_waitcnt lgkmcnt(0)
	s_waitcnt lgkmcnt(0)
	s_add_i32 s10, s10, s46
	s_cmp_ge_i32 s10, s1
	s_nop 7
	v_mul_f32_e32 v137, 0xbfb8aa3b, v114
	v_exp_f32_e32 v137, v137
	v_add_u32_e32 v136, s14, v182
	v_add_f32_e32 v137, 1.0, v137
	v_rcp_f32_e32 v138, v137
	v_mul_f32_e32 v137, 0xbfb8aa3b, v115
	v_exp_f32_e32 v137, v137
	s_nop 0
	v_add_f32_e32 v137, 1.0, v137
	v_rcp_f32_e32 v139, v137
	v_or_b32_e32 v130, s15, v173
	v_ashrrev_i32_e32 v132, 1, v130
	v_ashrrev_i32_e32 v133, 31, v132
	v_pk_mul_f32 v[114:115], v[114:115], v[138:139]
	v_mov_b64_e32 v[130:131], s[40:41]
	v_mad_i64_i32 v[134:135], s[2:3], v136, s5, v[130:131]
	s_nop 4
	v_pk_mul_f32 v[114:115], v[98:99], v[114:115]
	v_mul_f32_e32 v98, 0xbfb8aa3b, v116
	v_mul_f32_e32 v99, 0xbfb8aa3b, v117
	v_exp_f32_e32 v98, v98
	v_exp_f32_e32 v99, v99
	v_cvt_pk_bf16_f32 v114, v114, v115
	v_add_f32_e32 v98, 1.0, v98
	v_add_f32_e32 v99, 1.0, v99
	v_rcp_f32_e32 v98, v98
	v_rcp_f32_e32 v99, v99
	s_nop 0
	v_pk_mul_f32 v[98:99], v[116:117], v[98:99]
	s_nop 0
	v_pk_mul_f32 v[100:101], v[100:101], v[98:99]
	v_mul_f32_e32 v98, 0xbfb8aa3b, v118
	v_mul_f32_e32 v99, 0xbfb8aa3b, v119
	v_exp_f32_e32 v98, v98
	v_exp_f32_e32 v99, v99
	v_cvt_pk_bf16_f32 v115, v100, v101
	v_add_f32_e32 v98, 1.0, v98
	v_add_f32_e32 v99, 1.0, v99
	v_rcp_f32_e32 v98, v98
	v_rcp_f32_e32 v99, v99
	s_nop 0
	v_pk_mul_f32 v[98:99], v[118:119], v[98:99]
	s_nop 0
	v_pk_mul_f32 v[102:103], v[102:103], v[98:99]
	v_mul_f32_e32 v98, 0xbfb8aa3b, v120
	v_cvt_pk_bf16_f32 v100, v102, v103
	v_mul_f32_e32 v102, 0xbfb8aa3b, v82
	v_mul_f32_e32 v103, 0xbfb8aa3b, v83
	v_exp_f32_e32 v102, v102
	v_exp_f32_e32 v103, v103
	v_mul_f32_e32 v99, 0xbfb8aa3b, v121
	v_exp_f32_e32 v98, v98
	v_add_f32_e32 v102, 1.0, v102
	v_add_f32_e32 v103, 1.0, v103
	v_rcp_f32_e32 v102, v102
	v_rcp_f32_e32 v103, v103
	v_exp_f32_e32 v99, v99
	v_add_f32_e32 v98, 1.0, v98
	v_rcp_f32_e32 v98, v98
	v_pk_mul_f32 v[82:83], v[82:83], v[102:103]
	v_add_f32_e32 v99, 1.0, v99
	v_pk_mul_f32 v[66:67], v[66:67], v[82:83]
	v_mul_f32_e32 v82, 0xbfb8aa3b, v84
	v_mul_f32_e32 v83, 0xbfb8aa3b, v85
	v_exp_f32_e32 v82, v82
	v_exp_f32_e32 v83, v83
	v_cvt_pk_bf16_f32 v66, v66, v67
	v_rcp_f32_e32 v99, v99
	v_add_f32_e32 v82, 1.0, v82
	v_add_f32_e32 v83, 1.0, v83
	v_rcp_f32_e32 v82, v82
	v_rcp_f32_e32 v83, v83
	v_pk_mul_f32 v[98:99], v[120:121], v[98:99]
	v_pk_mul_f32 v[82:83], v[84:85], v[82:83]
	s_nop 0
	v_pk_mul_f32 v[68:69], v[68:69], v[82:83]
	v_mul_f32_e32 v82, 0xbfb8aa3b, v86
	v_cvt_pk_bf16_f32 v67, v68, v69
	v_mul_f32_e32 v68, 0xbfb8aa3b, v50
	v_mul_f32_e32 v69, 0xbfb8aa3b, v51
	v_exp_f32_e32 v68, v68
	v_exp_f32_e32 v69, v69
	v_mul_f32_e32 v83, 0xbfb8aa3b, v87
	v_exp_f32_e32 v82, v82
	v_add_f32_e32 v68, 1.0, v68
	v_add_f32_e32 v69, 1.0, v69
	v_rcp_f32_e32 v68, v68
	v_rcp_f32_e32 v69, v69
	v_exp_f32_e32 v83, v83
	v_add_f32_e32 v82, 1.0, v82
	v_rcp_f32_e32 v82, v82
	v_pk_mul_f32 v[50:51], v[50:51], v[68:69]
	v_add_f32_e32 v83, 1.0, v83
	v_pk_mul_f32 v[34:35], v[34:35], v[50:51]
	v_mul_f32_e32 v50, 0xbfb8aa3b, v52
	v_mul_f32_e32 v51, 0xbfb8aa3b, v53
	v_exp_f32_e32 v50, v50
	v_exp_f32_e32 v51, v51
	v_cvt_pk_bf16_f32 v34, v34, v35
	v_rcp_f32_e32 v83, v83
	v_add_f32_e32 v50, 1.0, v50
	v_add_f32_e32 v51, 1.0, v51
	v_rcp_f32_e32 v50, v50
	v_rcp_f32_e32 v51, v51
	v_pk_mul_f32 v[82:83], v[86:87], v[82:83]
	v_pk_mul_f32 v[104:105], v[104:105], v[98:99]
	v_pk_mul_f32 v[70:71], v[70:71], v[82:83]
	v_pk_mul_f32 v[50:51], v[52:53], v[50:51]
	v_mul_f32_e32 v82, 0xbfb8aa3b, v88
	v_pk_mul_f32 v[36:37], v[36:37], v[50:51]
	v_mul_f32_e32 v50, 0xbfb8aa3b, v54
	v_cvt_pk_bf16_f32 v35, v36, v37
	v_mul_f32_e32 v36, 0xbfb8aa3b, v18
	v_mul_f32_e32 v37, 0xbfb8aa3b, v19
	v_exp_f32_e32 v36, v36
	v_exp_f32_e32 v37, v37
	v_mul_f32_e32 v51, 0xbfb8aa3b, v55
	v_exp_f32_e32 v50, v50
	v_add_f32_e32 v36, 1.0, v36
	v_add_f32_e32 v37, 1.0, v37
	v_rcp_f32_e32 v36, v36
	v_rcp_f32_e32 v37, v37
	v_exp_f32_e32 v51, v51
	v_mul_f32_e32 v83, 0xbfb8aa3b, v89
	v_exp_f32_e32 v82, v82
	v_pk_mul_f32 v[18:19], v[18:19], v[36:37]
	v_exp_f32_e32 v83, v83
	v_pk_mul_f32 v[2:3], v[2:3], v[18:19]
	v_mul_f32_e32 v18, 0xbfb8aa3b, v20
	v_mul_f32_e32 v19, 0xbfb8aa3b, v21
	v_exp_f32_e32 v18, v18
	v_exp_f32_e32 v19, v19
	v_add_f32_e32 v50, 1.0, v50
	v_add_f32_e32 v51, 1.0, v51
	v_add_f32_e32 v18, 1.0, v18
	v_add_f32_e32 v19, 1.0, v19
	v_rcp_f32_e32 v18, v18
	v_rcp_f32_e32 v19, v19
	v_rcp_f32_e32 v50, v50
	v_rcp_f32_e32 v51, v51
	v_mul_f32_e32 v98, 0xbfb8aa3b, v122
	v_pk_mul_f32 v[18:19], v[20:21], v[18:19]
	v_mul_f32_e32 v99, 0xbfb8aa3b, v123
	v_pk_mul_f32 v[4:5], v[4:5], v[18:19]
	v_mul_f32_e32 v18, 0xbfb8aa3b, v22
	v_mul_f32_e32 v19, 0xbfb8aa3b, v23
	v_exp_f32_e32 v18, v18
	v_exp_f32_e32 v19, v19
	v_exp_f32_e32 v98, v98
	v_exp_f32_e32 v99, v99
	v_add_f32_e32 v82, 1.0, v82
	v_add_f32_e32 v83, 1.0, v83
	v_rcp_f32_e32 v82, v82
	v_rcp_f32_e32 v83, v83
	v_pk_mul_f32 v[50:51], v[54:55], v[50:51]
	v_add_f32_e32 v18, 1.0, v18
	v_pk_mul_f32 v[38:39], v[38:39], v[50:51]
	v_mul_f32_e32 v50, 0xbfb8aa3b, v56
	v_mul_f32_e32 v51, 0xbfb8aa3b, v57
	v_exp_f32_e32 v50, v50
	v_exp_f32_e32 v51, v51
	v_add_f32_e32 v19, 1.0, v19
	v_add_f32_e32 v98, 1.0, v98
	v_add_f32_e32 v99, 1.0, v99
	v_rcp_f32_e32 v18, v18
	v_rcp_f32_e32 v19, v19
	v_rcp_f32_e32 v98, v98
	v_rcp_f32_e32 v99, v99
	v_pk_mul_f32 v[82:83], v[88:89], v[82:83]
	v_add_f32_e32 v50, 1.0, v50
	v_pk_mul_f32 v[72:73], v[72:73], v[82:83]
	v_mul_f32_e32 v82, 0xbfb8aa3b, v90
	v_mul_f32_e32 v83, 0xbfb8aa3b, v91
	v_exp_f32_e32 v82, v82
	v_exp_f32_e32 v83, v83
	v_add_f32_e32 v51, 1.0, v51
	v_rcp_f32_e32 v50, v50
	v_rcp_f32_e32 v51, v51
	v_pk_mul_f32 v[18:19], v[22:23], v[18:19]
	v_pk_mul_f32 v[98:99], v[122:123], v[98:99]
	v_pk_mul_f32 v[6:7], v[6:7], v[18:19]
	v_mul_f32_e32 v18, 0xbfb8aa3b, v24
	v_mul_f32_e32 v19, 0xbfb8aa3b, v25
	v_pk_mul_f32 v[106:107], v[106:107], v[98:99]
	v_mul_f32_e32 v98, 0xbfb8aa3b, v124
	v_mul_f32_e32 v99, 0xbfb8aa3b, v125
	v_exp_f32_e32 v18, v18
	v_exp_f32_e32 v19, v19
	v_exp_f32_e32 v98, v98
	v_exp_f32_e32 v99, v99
	v_add_f32_e32 v82, 1.0, v82
	v_add_f32_e32 v83, 1.0, v83
	v_rcp_f32_e32 v82, v82
	v_rcp_f32_e32 v83, v83
	v_pk_mul_f32 v[50:51], v[56:57], v[50:51]
	v_add_f32_e32 v18, 1.0, v18
	v_pk_mul_f32 v[40:41], v[40:41], v[50:51]
	v_mul_f32_e32 v50, 0xbfb8aa3b, v58
	v_mul_f32_e32 v51, 0xbfb8aa3b, v59
	v_exp_f32_e32 v50, v50
	v_exp_f32_e32 v51, v51
	v_add_f32_e32 v19, 1.0, v19
	v_add_f32_e32 v98, 1.0, v98
	v_add_f32_e32 v99, 1.0, v99
	v_rcp_f32_e32 v18, v18
	v_rcp_f32_e32 v19, v19
	v_rcp_f32_e32 v98, v98
	v_rcp_f32_e32 v99, v99
	v_pk_mul_f32 v[82:83], v[90:91], v[82:83]
	v_add_f32_e32 v50, 1.0, v50
	v_pk_mul_f32 v[74:75], v[74:75], v[82:83]
	v_mul_f32_e32 v82, 0xbfb8aa3b, v92
	v_mul_f32_e32 v83, 0xbfb8aa3b, v93
	v_exp_f32_e32 v82, v82
	v_exp_f32_e32 v83, v83
	v_add_f32_e32 v51, 1.0, v51
	v_rcp_f32_e32 v50, v50
	v_rcp_f32_e32 v51, v51
	v_pk_mul_f32 v[18:19], v[24:25], v[18:19]
	v_pk_mul_f32 v[98:99], v[124:125], v[98:99]
	v_pk_mul_f32 v[8:9], v[8:9], v[18:19]
	v_mul_f32_e32 v18, 0xbfb8aa3b, v26
	v_mul_f32_e32 v19, 0xbfb8aa3b, v27
	v_pk_mul_f32 v[108:109], v[108:109], v[98:99]
	v_mul_f32_e32 v98, 0xbfb8aa3b, v126
	v_mul_f32_e32 v99, 0xbfb8aa3b, v127
	v_exp_f32_e32 v18, v18
	v_exp_f32_e32 v19, v19
	v_exp_f32_e32 v98, v98
	v_exp_f32_e32 v99, v99
	v_add_f32_e32 v82, 1.0, v82
	v_add_f32_e32 v83, 1.0, v83
	v_rcp_f32_e32 v82, v82
	v_rcp_f32_e32 v83, v83
	v_pk_mul_f32 v[50:51], v[58:59], v[50:51]
	v_add_f32_e32 v18, 1.0, v18
	v_pk_mul_f32 v[42:43], v[42:43], v[50:51]
	v_mul_f32_e32 v50, 0xbfb8aa3b, v60
	v_mul_f32_e32 v51, 0xbfb8aa3b, v61
	v_exp_f32_e32 v50, v50
	v_exp_f32_e32 v51, v51
	v_add_f32_e32 v19, 1.0, v19
	v_add_f32_e32 v98, 1.0, v98
	v_add_f32_e32 v99, 1.0, v99
	v_rcp_f32_e32 v18, v18
	v_rcp_f32_e32 v19, v19
	v_rcp_f32_e32 v98, v98
	v_rcp_f32_e32 v99, v99
	v_pk_mul_f32 v[82:83], v[92:93], v[82:83]
	v_add_f32_e32 v50, 1.0, v50
	v_pk_mul_f32 v[76:77], v[76:77], v[82:83]
	v_mul_f32_e32 v82, 0xbfb8aa3b, v94
	v_mul_f32_e32 v83, 0xbfb8aa3b, v95
	v_exp_f32_e32 v82, v82
	v_exp_f32_e32 v83, v83
	v_add_f32_e32 v51, 1.0, v51
	v_rcp_f32_e32 v50, v50
	v_rcp_f32_e32 v51, v51
	v_pk_mul_f32 v[18:19], v[26:27], v[18:19]
	v_pk_mul_f32 v[98:99], v[126:127], v[98:99]
	v_pk_mul_f32 v[10:11], v[10:11], v[18:19]
	v_mul_f32_e32 v18, 0xbfb8aa3b, v28
	v_mul_f32_e32 v19, 0xbfb8aa3b, v29
	v_pk_mul_f32 v[110:111], v[110:111], v[98:99]
	v_mul_f32_e32 v98, 0xbfb8aa3b, v128
	v_mul_f32_e32 v99, 0xbfb8aa3b, v129
	v_exp_f32_e32 v18, v18
	v_exp_f32_e32 v19, v19
	v_exp_f32_e32 v98, v98
	v_exp_f32_e32 v99, v99
	v_add_f32_e32 v82, 1.0, v82
	v_add_f32_e32 v83, 1.0, v83
	v_rcp_f32_e32 v82, v82
	v_rcp_f32_e32 v83, v83
	v_pk_mul_f32 v[50:51], v[60:61], v[50:51]
	v_add_f32_e32 v18, 1.0, v18
	v_pk_mul_f32 v[44:45], v[44:45], v[50:51]
	v_mul_f32_e32 v50, 0xbfb8aa3b, v62
	v_mul_f32_e32 v51, 0xbfb8aa3b, v63
	v_exp_f32_e32 v50, v50
	v_exp_f32_e32 v51, v51
	v_add_f32_e32 v19, 1.0, v19
	v_add_f32_e32 v98, 1.0, v98
	v_add_f32_e32 v99, 1.0, v99
	v_rcp_f32_e32 v18, v18
	v_rcp_f32_e32 v19, v19
	v_rcp_f32_e32 v98, v98
	v_rcp_f32_e32 v99, v99
	v_pk_mul_f32 v[82:83], v[94:95], v[82:83]
	v_add_f32_e32 v50, 1.0, v50
	v_pk_mul_f32 v[78:79], v[78:79], v[82:83]
	v_mul_f32_e32 v82, 0xbfb8aa3b, v96
	v_mul_f32_e32 v83, 0xbfb8aa3b, v97
	v_exp_f32_e32 v82, v82
	v_exp_f32_e32 v83, v83
	v_add_f32_e32 v51, 1.0, v51
	v_rcp_f32_e32 v50, v50
	v_rcp_f32_e32 v51, v51
	v_pk_mul_f32 v[18:19], v[28:29], v[18:19]
	v_pk_mul_f32 v[98:99], v[128:129], v[98:99]
	v_pk_mul_f32 v[12:13], v[12:13], v[18:19]
	v_mul_f32_e32 v18, 0xbfb8aa3b, v30
	v_mul_f32_e32 v19, 0xbfb8aa3b, v31
	v_pk_mul_f32 v[112:113], v[112:113], v[98:99]
	v_lshlrev_b64 v[98:99], 1, v[132:133]
	v_exp_f32_e32 v18, v18
	v_exp_f32_e32 v19, v19
	v_lshl_add_u64 v[116:117], v[134:135], 0, v[98:99]
	v_add_f32_e32 v82, 1.0, v82
	v_add_f32_e32 v83, 1.0, v83
	v_lshl_add_u64 v[116:117], v[116:117], 0, v[0:1]
	v_cvt_pk_bf16_f32 v101, v104, v105
	v_rcp_f32_e32 v82, v82
	v_rcp_f32_e32 v83, v83
	v_pk_mul_f32 v[50:51], v[62:63], v[50:51]
	global_store_dwordx2 v[116:117], v[100:101], off offset:16
	v_cvt_pk_bf16_f32 v100, v106, v107
	v_cvt_pk_bf16_f32 v101, v108, v109
	v_pk_mul_f32 v[46:47], v[46:47], v[50:51]
	v_mul_f32_e32 v50, 0xbfb8aa3b, v64
	v_mul_f32_e32 v51, 0xbfb8aa3b, v65
	global_store_dwordx2 v[116:117], v[100:101], off offset:32
	v_cvt_pk_bf16_f32 v100, v110, v111
	v_cvt_pk_bf16_f32 v101, v112, v113
	v_exp_f32_e32 v50, v50
	v_exp_f32_e32 v51, v51
	v_add_f32_e32 v18, 1.0, v18
	v_add_f32_e32 v19, 1.0, v19
	global_store_dwordx2 v[116:117], v[100:101], off offset:48
	v_or_b32_e32 v100, 32, v136
	v_rcp_f32_e32 v18, v18
	v_rcp_f32_e32 v19, v19
	v_mad_i64_i32 v[100:101], s[2:3], v100, s5, v[130:131]
	v_pk_mul_f32 v[82:83], v[96:97], v[82:83]
	v_add_f32_e32 v50, 1.0, v50
	v_pk_mul_f32 v[80:81], v[80:81], v[82:83]
	v_lshl_add_u64 v[82:83], v[100:101], 0, v[98:99]
	v_lshl_add_u64 v[82:83], v[82:83], 0, v[0:1]
	v_add_f32_e32 v51, 1.0, v51
	global_store_dwordx2 v[82:83], v[66:67], off
	v_cvt_pk_bf16_f32 v66, v70, v71
	v_cvt_pk_bf16_f32 v67, v72, v73
	v_rcp_f32_e32 v50, v50
	v_rcp_f32_e32 v51, v51
	v_pk_mul_f32 v[18:19], v[30:31], v[18:19]
	global_store_dwordx2 v[82:83], v[66:67], off offset:16
	v_cvt_pk_bf16_f32 v66, v74, v75
	v_cvt_pk_bf16_f32 v67, v76, v77
	v_pk_mul_f32 v[14:15], v[14:15], v[18:19]
	v_mul_f32_e32 v18, 0xbfb8aa3b, v32
	v_mul_f32_e32 v19, 0xbfb8aa3b, v33
	global_store_dwordx2 v[82:83], v[66:67], off offset:32
	v_cvt_pk_bf16_f32 v66, v78, v79
	v_cvt_pk_bf16_f32 v67, v80, v81
	v_exp_f32_e32 v18, v18
	v_exp_f32_e32 v19, v19
	global_store_dwordx2 v[82:83], v[66:67], off offset:48
	v_or_b32_e32 v66, 64, v136
	v_mad_i64_i32 v[66:67], s[2:3], v66, s5, v[130:131]
	v_pk_mul_f32 v[50:51], v[64:65], v[50:51]
	v_add_f32_e32 v18, 1.0, v18
	v_pk_mul_f32 v[48:49], v[48:49], v[50:51]
	v_lshl_add_u64 v[50:51], v[66:67], 0, v[98:99]
	v_lshl_add_u64 v[50:51], v[50:51], 0, v[0:1]
	v_add_f32_e32 v19, 1.0, v19
	global_store_dwordx2 v[50:51], v[34:35], off
	v_cvt_pk_bf16_f32 v34, v38, v39
	v_cvt_pk_bf16_f32 v35, v40, v41
	v_rcp_f32_e32 v18, v18
	v_rcp_f32_e32 v19, v19
	global_store_dwordx2 v[50:51], v[34:35], off offset:16
	v_cvt_pk_bf16_f32 v34, v42, v43
	v_cvt_pk_bf16_f32 v35, v44, v45
	global_store_dwordx2 v[50:51], v[34:35], off offset:32
	v_cvt_pk_bf16_f32 v34, v46, v47
	v_cvt_pk_bf16_f32 v35, v48, v49
	global_store_dwordx2 v[50:51], v[34:35], off offset:48
	v_or_b32_e32 v34, 0x60, v136
	v_mad_i64_i32 v[34:35], s[2:3], v34, s5, v[130:131]
	v_pk_mul_f32 v[18:19], v[32:33], v[18:19]
	v_cvt_pk_bf16_f32 v2, v2, v3
	v_pk_mul_f32 v[16:17], v[16:17], v[18:19]
	v_lshl_add_u64 v[18:19], v[34:35], 0, v[98:99]
	v_lshl_add_u64 v[18:19], v[18:19], 0, v[0:1]
	v_cvt_pk_bf16_f32 v3, v4, v5
	global_store_dwordx2 v[18:19], v[2:3], off
	v_cvt_pk_bf16_f32 v2, v6, v7
	v_cvt_pk_bf16_f32 v3, v8, v9
	global_store_dwordx2 v[18:19], v[2:3], off offset:16
	v_cvt_pk_bf16_f32 v2, v10, v11
	v_cvt_pk_bf16_f32 v3, v12, v13
	global_store_dwordx2 v[18:19], v[2:3], off offset:32
	v_cvt_pk_bf16_f32 v2, v14, v15
	v_cvt_pk_bf16_f32 v3, v16, v17
	global_store_dwordx2 v[116:117], v[114:115], off
	global_store_dwordx2 v[18:19], v[2:3], off offset:48
	s_cbranch_scc0 .LBB0_53
